# FoX log-forget cumsum phase: all 64 per-lane loads issued up front and kept in registers (single pass, same summation order) instead of two serialized load passes
# speedup vs baseline: 1.0195x; 1.0103x over previous
; __device__ __forceinline__ int tid_fresh() { int t = threadIdx.x; asm volatile("" : "+v"(t)); return t; }
; #define GAS __attribute__((address_space(1)))
; __device__ __forceinline__ void phase_scan(const Params& P) {
;   const int tid = tid_fresh(); const int lane = tid & 63, gw = blockIdx.x * (NTHREADS / 64) + (tid >> 6), nw = gridDim.x * (NTHREADS / 64);
;   for (int seq = gw; seq < 128; seq += nw) {
;     const int b = seq >> 4, h = seq & 15;
;     GAS const float* src = (GAS const float*)(P.logf + ((size_t)b * SEQ + lane * 64) * 16 + h);
;     float tot = 0.f;
; #pragma unroll 16
;     for (int i = 0; i < 64; ++i) tot += src[(size_t)i * 16];
;     float inc = tot;
; #pragma unroll
;     for (int d = 1; d < 64; d <<= 1) { const float o = __shfl_up(inc, d); if (lane >= d) inc += o; }
.LBB0_1558:
	flat_load_dwordx2 v[10:11], v[8:9] offset:264
	flat_load_dwordx2 v[12:13], v[8:9] offset:272
	v_ashrrev_i32_e32 v14, 4, v0
	v_ashrrev_i32_e32 v15, 31, v14
	v_lshlrev_b64 v[14:15], 18, v[14:15]
	v_and_b32_e32 v1, 15, v0
	v_lshlrev_b32_e32 v4, 2, v1
	s_waitcnt vmcnt(0) lgkmcnt(0)
	v_lshl_add_u64 v[10:11], v[10:11], 0, v[14:15]
	v_lshl_add_u64 v[10:11], v[10:11], 0, v[2:3]
	v_lshl_add_u64 v[10:11], v[10:11], 0, v[4:5]
	v_lshl_add_u64 v[12:13], v[12:13], 0, v[6:7]
	global_load_dword v32, v[10:11], off
	global_load_dword v33, v[10:11], off offset:64
	global_load_dword v34, v[10:11], off offset:128
	global_load_dword v35, v[10:11], off offset:192
	global_load_dword v36, v[10:11], off offset:256
	global_load_dword v37, v[10:11], off offset:320
	global_load_dword v38, v[10:11], off offset:384
	global_load_dword v39, v[10:11], off offset:448
	global_load_dword v40, v[10:11], off offset:512
	global_load_dword v41, v[10:11], off offset:576
	global_load_dword v42, v[10:11], off offset:640
	global_load_dword v43, v[10:11], off offset:704
	global_load_dword v44, v[10:11], off offset:768
	global_load_dword v45, v[10:11], off offset:832
	global_load_dword v46, v[10:11], off offset:896
	global_load_dword v47, v[10:11], off offset:960
	global_load_dword v48, v[10:11], off offset:1024
	global_load_dword v49, v[10:11], off offset:1088
	global_load_dword v50, v[10:11], off offset:1152
	global_load_dword v51, v[10:11], off offset:1216
	global_load_dword v52, v[10:11], off offset:1280
	global_load_dword v53, v[10:11], off offset:1344
	global_load_dword v54, v[10:11], off offset:1408
	global_load_dword v55, v[10:11], off offset:1472
	global_load_dword v56, v[10:11], off offset:1536
	global_load_dword v57, v[10:11], off offset:1600
	global_load_dword v58, v[10:11], off offset:1664
	global_load_dword v59, v[10:11], off offset:1728
	global_load_dword v60, v[10:11], off offset:1792
	global_load_dword v61, v[10:11], off offset:1856
	global_load_dword v62, v[10:11], off offset:1920
	global_load_dword v63, v[10:11], off offset:1984
	global_load_dword v64, v[10:11], off offset:2048
	global_load_dword v65, v[10:11], off offset:2112
	global_load_dword v66, v[10:11], off offset:2176
	global_load_dword v67, v[10:11], off offset:2240
	global_load_dword v68, v[10:11], off offset:2304
	global_load_dword v69, v[10:11], off offset:2368
	global_load_dword v70, v[10:11], off offset:2432
	global_load_dword v71, v[10:11], off offset:2496
	global_load_dword v72, v[10:11], off offset:2560
	global_load_dword v73, v[10:11], off offset:2624
	global_load_dword v74, v[10:11], off offset:2688
	global_load_dword v75, v[10:11], off offset:2752
	global_load_dword v76, v[10:11], off offset:2816
	global_load_dword v77, v[10:11], off offset:2880
	global_load_dword v78, v[10:11], off offset:2944
	global_load_dword v79, v[10:11], off offset:3008
	global_load_dword v80, v[10:11], off offset:3072
	global_load_dword v81, v[10:11], off offset:3136
	global_load_dword v82, v[10:11], off offset:3200
	global_load_dword v83, v[10:11], off offset:3264
	global_load_dword v84, v[10:11], off offset:3328
	global_load_dword v85, v[10:11], off offset:3392
	global_load_dword v86, v[10:11], off offset:3456
	global_load_dword v87, v[10:11], off offset:3520
	global_load_dword v88, v[10:11], off offset:3584
	global_load_dword v89, v[10:11], off offset:3648
	global_load_dword v90, v[10:11], off offset:3712
	global_load_dword v91, v[10:11], off offset:3776
	global_load_dword v92, v[10:11], off offset:3840
	global_load_dword v93, v[10:11], off offset:3904
	global_load_dword v94, v[10:11], off offset:3968
	global_load_dword v95, v[10:11], off offset:4032
	v_mov_b32_e32 v1, 0
	s_waitcnt vmcnt(63)
	v_add_f32_e32 v1, v1, v32
	s_waitcnt vmcnt(62)
	v_add_f32_e32 v1, v1, v33
	s_waitcnt vmcnt(61)
	v_add_f32_e32 v1, v1, v34
	s_waitcnt vmcnt(60)
	v_add_f32_e32 v1, v1, v35
	s_waitcnt vmcnt(59)
	v_add_f32_e32 v1, v1, v36
	s_waitcnt vmcnt(58)
	v_add_f32_e32 v1, v1, v37
	s_waitcnt vmcnt(57)
	v_add_f32_e32 v1, v1, v38
	s_waitcnt vmcnt(56)
	v_add_f32_e32 v1, v1, v39
	s_waitcnt vmcnt(55)
	v_add_f32_e32 v1, v1, v40
	s_waitcnt vmcnt(54)
	v_add_f32_e32 v1, v1, v41
	s_waitcnt vmcnt(53)
	v_add_f32_e32 v1, v1, v42
	s_waitcnt vmcnt(52)
	v_add_f32_e32 v1, v1, v43
	s_waitcnt vmcnt(51)
	v_add_f32_e32 v1, v1, v44
	s_waitcnt vmcnt(50)
	v_add_f32_e32 v1, v1, v45
	s_waitcnt vmcnt(49)
	v_add_f32_e32 v1, v1, v46
	s_waitcnt vmcnt(48)
	v_add_f32_e32 v1, v1, v47
	s_waitcnt vmcnt(47)
	v_add_f32_e32 v1, v1, v48
	s_waitcnt vmcnt(46)
	v_add_f32_e32 v1, v1, v49
	s_waitcnt vmcnt(45)
	v_add_f32_e32 v1, v1, v50
	s_waitcnt vmcnt(44)
	v_add_f32_e32 v1, v1, v51
	s_waitcnt vmcnt(43)
	v_add_f32_e32 v1, v1, v52
	s_waitcnt vmcnt(42)
	v_add_f32_e32 v1, v1, v53
	s_waitcnt vmcnt(41)
	v_add_f32_e32 v1, v1, v54
	s_waitcnt vmcnt(40)
	v_add_f32_e32 v1, v1, v55
	s_waitcnt vmcnt(39)
	v_add_f32_e32 v1, v1, v56
	s_waitcnt vmcnt(38)
	v_add_f32_e32 v1, v1, v57
	s_waitcnt vmcnt(37)
	v_add_f32_e32 v1, v1, v58
	s_waitcnt vmcnt(36)
	v_add_f32_e32 v1, v1, v59
	s_waitcnt vmcnt(35)
	v_add_f32_e32 v1, v1, v60
	s_waitcnt vmcnt(34)
	v_add_f32_e32 v1, v1, v61
	s_waitcnt vmcnt(33)
	v_add_f32_e32 v1, v1, v62
	s_waitcnt vmcnt(32)
	v_add_f32_e32 v1, v1, v63
	s_waitcnt vmcnt(31)
	v_add_f32_e32 v1, v1, v64
	s_waitcnt vmcnt(30)
	v_add_f32_e32 v1, v1, v65
	s_waitcnt vmcnt(29)
	v_add_f32_e32 v1, v1, v66
	s_waitcnt vmcnt(28)
	v_add_f32_e32 v1, v1, v67
	s_waitcnt vmcnt(27)
	v_add_f32_e32 v1, v1, v68
	s_waitcnt vmcnt(26)
	v_add_f32_e32 v1, v1, v69
	s_waitcnt vmcnt(25)
	v_add_f32_e32 v1, v1, v70
	s_waitcnt vmcnt(24)
	v_add_f32_e32 v1, v1, v71
	s_waitcnt vmcnt(23)
	v_add_f32_e32 v1, v1, v72
	s_waitcnt vmcnt(22)
; #define GAS __attribute__((address_space(1)))
; __device__ __forceinline__ void phase_scan(const Params& P) {
;     ...
;     for (int i = 0; i < 64; ++i) tot += src[(size_t)i * 16];
;     float inc = tot;
; #pragma unroll
;     for (int d = 1; d < 64; d <<= 1) { const float o = __shfl_up(inc, d); if (lane >= d) inc += o; }
;     float run = inc - tot;
;     float* dst = P.logc + (size_t)seq * SEQ + lane * 64;
; #pragma unroll 4
;     for (int i = 0; i < 64; i += 4) {
;       f32x4 o;
;       run += src[(size_t)i * 16]; o[0] = -run * LOG2E;
;       run += src[(size_t)(i + 1) * 16]; o[1] = -run * LOG2E;
;       run += src[(size_t)(i + 2) * 16]; o[2] = -run * LOG2E;
;       run += src[(size_t)(i + 3) * 16]; o[3] = -run * LOG2E;
;       *(GAS f32x4*)(dst + i) = o;
;     }
	v_add_f32_e32 v1, v1, v73
	s_waitcnt vmcnt(21)
	v_add_f32_e32 v1, v1, v74
	s_waitcnt vmcnt(20)
	v_add_f32_e32 v1, v1, v75
	s_waitcnt vmcnt(19)
	v_add_f32_e32 v1, v1, v76
	s_waitcnt vmcnt(18)
	v_add_f32_e32 v1, v1, v77
	s_waitcnt vmcnt(17)
	v_add_f32_e32 v1, v1, v78
	s_waitcnt vmcnt(16)
	v_add_f32_e32 v1, v1, v79
	s_waitcnt vmcnt(15)
	v_add_f32_e32 v1, v1, v80
	s_waitcnt vmcnt(14)
	v_add_f32_e32 v1, v1, v81
	s_waitcnt vmcnt(13)
	v_add_f32_e32 v1, v1, v82
	s_waitcnt vmcnt(12)
	v_add_f32_e32 v1, v1, v83
	s_waitcnt vmcnt(11)
	v_add_f32_e32 v1, v1, v84
	s_waitcnt vmcnt(10)
	v_add_f32_e32 v1, v1, v85
	s_waitcnt vmcnt(9)
	v_add_f32_e32 v1, v1, v86
	s_waitcnt vmcnt(8)
	v_add_f32_e32 v1, v1, v87
	s_waitcnt vmcnt(7)
	v_add_f32_e32 v1, v1, v88
	s_waitcnt vmcnt(6)
	v_add_f32_e32 v1, v1, v89
	s_waitcnt vmcnt(5)
	v_add_f32_e32 v1, v1, v90
	s_waitcnt vmcnt(4)
	v_add_f32_e32 v1, v1, v91
	s_waitcnt vmcnt(3)
	v_add_f32_e32 v1, v1, v92
	s_waitcnt vmcnt(2)
	v_add_f32_e32 v1, v1, v93
	s_waitcnt vmcnt(1)
	v_add_f32_e32 v1, v1, v94
	s_waitcnt vmcnt(0)
	v_add_f32_e32 v1, v1, v95
	ds_bpermute_b32 v4, v16, v1
	s_waitcnt lgkmcnt(0)
	v_add_f32_e32 v4, v1, v4
	v_cndmask_b32_e32 v4, v4, v1, vcc
	ds_bpermute_b32 v14, v17, v4
	s_waitcnt lgkmcnt(0)
	v_add_f32_e32 v14, v4, v14
	v_cndmask_b32_e64 v4, v14, v4, s[6:7]
	ds_bpermute_b32 v14, v18, v4
	s_waitcnt lgkmcnt(0)
	v_add_f32_e32 v14, v4, v14
	v_cndmask_b32_e64 v4, v14, v4, s[8:9]
	ds_bpermute_b32 v14, v19, v4
	s_waitcnt lgkmcnt(0)
	v_add_f32_e32 v14, v4, v14
	v_cndmask_b32_e64 v4, v14, v4, s[10:11]
	ds_bpermute_b32 v14, v20, v4
	s_waitcnt lgkmcnt(0)
	v_add_f32_e32 v14, v4, v14
	v_cndmask_b32_e64 v4, v14, v4, s[12:13]
	ds_bpermute_b32 v14, v21, v4
	s_waitcnt lgkmcnt(0)
	v_add_f32_e32 v14, v4, v14
	v_cndmask_b32_e64 v4, v14, v4, s[14:15]
	v_sub_f32_e32 v15, v4, v1
	v_add_f32_e32 v32, v15, v32
	v_add_f32_e32 v33, v32, v33
	v_add_f32_e32 v34, v33, v34
	v_add_f32_e32 v35, v34, v35
	v_add_f32_e32 v36, v35, v36
	v_add_f32_e32 v37, v36, v37
	v_add_f32_e32 v38, v37, v38
	v_add_f32_e32 v39, v38, v39
	v_add_f32_e32 v40, v39, v40
	v_add_f32_e32 v41, v40, v41
	v_add_f32_e32 v42, v41, v42
	v_add_f32_e32 v43, v42, v43
	v_add_f32_e32 v44, v43, v44
	v_add_f32_e32 v45, v44, v45
	v_add_f32_e32 v46, v45, v46
	v_add_f32_e32 v47, v46, v47
	v_add_f32_e32 v48, v47, v48
	v_add_f32_e32 v49, v48, v49
	v_add_f32_e32 v50, v49, v50
	v_add_f32_e32 v51, v50, v51
	v_add_f32_e32 v52, v51, v52
	v_add_f32_e32 v53, v52, v53
	v_add_f32_e32 v54, v53, v54
	v_add_f32_e32 v55, v54, v55
	v_add_f32_e32 v56, v55, v56
	v_add_f32_e32 v57, v56, v57
	v_add_f32_e32 v58, v57, v58
	v_add_f32_e32 v59, v58, v59
	v_add_f32_e32 v60, v59, v60
	v_add_f32_e32 v61, v60, v61
	v_add_f32_e32 v62, v61, v62
	v_add_f32_e32 v63, v62, v63
	v_add_f32_e32 v64, v63, v64
	v_add_f32_e32 v65, v64, v65
	v_add_f32_e32 v66, v65, v66
	v_add_f32_e32 v67, v66, v67
	v_add_f32_e32 v68, v67, v68
	v_add_f32_e32 v69, v68, v69
	v_add_f32_e32 v70, v69, v70
	v_add_f32_e32 v71, v70, v71
	v_add_f32_e32 v72, v71, v72
	v_add_f32_e32 v73, v72, v73
	v_add_f32_e32 v74, v73, v74
	v_add_f32_e32 v75, v74, v75
	v_add_f32_e32 v76, v75, v76
	v_add_f32_e32 v77, v76, v77
	v_add_f32_e32 v78, v77, v78
	v_add_f32_e32 v79, v78, v79
	v_add_f32_e32 v80, v79, v80
	v_add_f32_e32 v81, v80, v81
	v_add_f32_e32 v82, v81, v82
	v_add_f32_e32 v83, v82, v83
	v_add_f32_e32 v84, v83, v84
	v_add_f32_e32 v85, v84, v85
	v_add_f32_e32 v86, v85, v86
	v_add_f32_e32 v87, v86, v87
	v_add_f32_e32 v88, v87, v88
	v_add_f32_e32 v89, v88, v89
	v_add_f32_e32 v90, v89, v90
	v_add_f32_e32 v91, v90, v91
	v_add_f32_e32 v92, v91, v92
	v_add_f32_e32 v93, v92, v93
	v_add_f32_e32 v94, v93, v94
	v_add_f32_e32 v95, v94, v95
	v_mul_f32_e32 v32, s28, v32
	v_mul_f32_e32 v33, s28, v33
	v_mul_f32_e32 v34, s28, v34
	v_mul_f32_e32 v35, s28, v35
	v_mul_f32_e32 v36, s28, v36
	v_mul_f32_e32 v37, s28, v37
	v_mul_f32_e32 v38, s28, v38
	v_mul_f32_e32 v39, s28, v39
	v_mul_f32_e32 v40, s28, v40
	v_mul_f32_e32 v41, s28, v41
	v_mul_f32_e32 v42, s28, v42
	v_mul_f32_e32 v43, s28, v43
	v_mul_f32_e32 v44, s28, v44
	v_mul_f32_e32 v45, s28, v45
	v_mul_f32_e32 v46, s28, v46
	v_mul_f32_e32 v47, s28, v47
	v_mul_f32_e32 v48, s28, v48
	v_mul_f32_e32 v49, s28, v49
	v_mul_f32_e32 v50, s28, v50
	v_mul_f32_e32 v51, s28, v51
	v_mul_f32_e32 v52, s28, v52
	v_mul_f32_e32 v53, s28, v53
	v_mul_f32_e32 v54, s28, v54
	v_mul_f32_e32 v55, s28, v55
	v_mul_f32_e32 v56, s28, v56
	v_mul_f32_e32 v57, s28, v57
	v_mul_f32_e32 v58, s28, v58
	v_mul_f32_e32 v59, s28, v59
	v_mul_f32_e32 v60, s28, v60
	v_mul_f32_e32 v61, s28, v61
	v_mul_f32_e32 v62, s28, v62
	v_mul_f32_e32 v63, s28, v63
	v_mul_f32_e32 v64, s28, v64
	v_mul_f32_e32 v65, s28, v65
	v_mul_f32_e32 v66, s28, v66
	v_mul_f32_e32 v67, s28, v67
	v_mul_f32_e32 v68, s28, v68
	v_mul_f32_e32 v69, s28, v69
	v_mul_f32_e32 v70, s28, v70
	v_mul_f32_e32 v71, s28, v71
	v_mul_f32_e32 v72, s28, v72
	v_mul_f32_e32 v73, s28, v73
	v_mul_f32_e32 v74, s28, v74
	v_mul_f32_e32 v75, s28, v75
	v_mul_f32_e32 v76, s28, v76
	v_mul_f32_e32 v77, s28, v77
	v_mul_f32_e32 v78, s28, v78
	v_mul_f32_e32 v79, s28, v79
	v_mul_f32_e32 v80, s28, v80
	v_mul_f32_e32 v81, s28, v81
	v_mul_f32_e32 v82, s28, v82
	v_mul_f32_e32 v83, s28, v83
	v_mul_f32_e32 v84, s28, v84
	v_mul_f32_e32 v85, s28, v85
	v_mul_f32_e32 v86, s28, v86
	v_mul_f32_e32 v87, s28, v87
	v_mul_f32_e32 v88, s28, v88
	v_mul_f32_e32 v89, s28, v89
	v_mul_f32_e32 v90, s28, v90
	v_mul_f32_e32 v91, s28, v91
	v_mul_f32_e32 v92, s28, v92
	v_mul_f32_e32 v93, s28, v93
	v_mul_f32_e32 v94, s28, v94
	v_mul_f32_e32 v95, s28, v95
	global_store_dwordx4 v[12:13], v[32:35], off offset:-48
	global_store_dwordx4 v[12:13], v[36:39], off offset:-32
	global_store_dwordx4 v[12:13], v[40:43], off offset:-16
	global_store_dwordx4 v[12:13], v[44:47], off
	global_store_dwordx4 v[12:13], v[48:51], off offset:16
	global_store_dwordx4 v[12:13], v[52:55], off offset:32
	global_store_dwordx4 v[12:13], v[56:59], off offset:48
	global_store_dwordx4 v[12:13], v[60:63], off offset:64
	global_store_dwordx4 v[12:13], v[64:67], off offset:80
	global_store_dwordx4 v[12:13], v[68:71], off offset:96
	global_store_dwordx4 v[12:13], v[72:75], off offset:112
	global_store_dwordx4 v[12:13], v[76:79], off offset:128
	global_store_dwordx4 v[12:13], v[80:83], off offset:144
	global_store_dwordx4 v[12:13], v[84:87], off offset:160
	global_store_dwordx4 v[12:13], v[88:91], off offset:176
	global_store_dwordx4 v[12:13], v[92:95], off offset:192
	v_add_u32_e32 v0, s40, v0
	v_cmp_lt_i32_e64 s[16:17], s29, v0
	s_or_b64 s[22:23], s[16:17], s[22:23]
	v_lshl_add_u64 v[6:7], v[6:7], 0, s[20:21]
	s_andn2_b64 exec, exec, s[22:23]
	s_cbranch_execnz .LBB0_1558
